# late weight conversion (ffn2/w_out to bf16) moved from P5 onto the 114 workgroups that idle during the last P3 GEMM round; on top of k10
# speedup vs baseline: 1.0310x; 1.0075x over previous
; #define PG8_WAIT_V(n) asm volatile("s_waitcnt vmcnt(" #n ")" ::: "memory")
; #define PG8_BAR __builtin_amdgcn_s_barrier()
; #define LAS __attribute__((address_space(3)))
; template <class Epi, class Sched, bool ALIGN_EPI = false, bool SP2 = false>
; __device__ __forceinline__ void gemm_phase(PG8_LAS unsigned char* lds, const Gemm g, const Sched& S, const Epi& E) {
;     ...
;     PG8_WAIT_V(0);
;     if constexpr (!ALIGN_EPI) { if (wr == 0) PG8_BAR; }
;     PG8_BAR;
; __device__ __forceinline__ void convert_weights(CArgsP a, LAS unsigned char* lds, int wave, int lane, int which, int gb, int NGB) {
;     unsigned char* ws = a->ws;
;     constexpr int I0 = 22 * 16, I1 = 4 * 44, I2 = 14 * 16, I3 = 4 * 16;
;     const int NIT = which == 0 ? I0 + I1 + I2 : I0 + I1 + I3;
;     for (int it = gb; it < NIT; it += NGB) {
;         int r = it;
;         if (r < I0) { const int pn = r >> 4, kb = r & 15;
;             convert_tile(which == 0 ? a->in[8] : a->in[28], 1024, 5632, which == 0 ? a->in[7] : a->in[27], (bf16_t*)(ws + (which == 0 ? WS_W1I : WS_W2I)), pn, 64 * kb, 0, lds, wave, lane); continue; }
;         r -= I0;
;         if (r < I1) { const int pn = r / 44, kb = r % 44; convert_tile(which == 0 ? a->in[9] : a->in[29], DFF, 1024, nullptr, (bf16_t*)(ws + (which == 0 ? WS_W1O : WS_W2O)), pn, 64 * kb, 1, lds, wave, lane); continue; }
;         r -= I1;
;         if (which == 0) { const int pn = r >> 4, kb = r & 15; convert_tile(a->in[11], 1024, 3336, a->in[10], (bf16_t*)(ws + WS_WIN), pn, 64 * kb, 2, lds, wave, lane); }
;         else { const int pn = r >> 4, kb = r & 15; convert_tile(a->in[12], 1024, 1024, nullptr, (bf16_t*)(ws + WS_WOUT), pn, 64 * kb, 1, lds, wave, lane); }
;     }
.LBB0_538:
	s_waitcnt vmcnt(0)
	v_readlane_b32 s92, v250, 21
	v_readlane_b32 s80, v250, 15
	v_readlane_b32 s82, v250, 13
	v_readlane_b32 s84, v250, 10
	v_readlane_b32 s88, v250, 6
	v_readlane_b32 s93, v250, 22
	v_readlane_b32 s78, v250, 19
	v_readlane_b32 s77, v250, 17
	v_readlane_b32 s81, v250, 16
	v_readlane_b32 s83, v250, 14
	v_readlane_b32 s79, v250, 12
	v_readlane_b32 s85, v250, 11
	v_readlane_b32 s86, v250, 8
	v_readlane_b32 s89, v250, 7
	s_barrier
	v_readlane_b32 s87, v250, 9
	s_mov_b64 s[18:19], s[92:93]
	s_load_dwordx2 s[14:15], s[92:93], 0xf8
	s_waitcnt lgkmcnt(0)
.Lcv_743:
	s_cmpk_eq_i32 s60, 0x100
	s_cselect_b64 s[66:67], -1, 0
	s_cmpk_lg_i32 s60, 0x100
	s_cselect_b64 s[16:17], -1, 0
	s_cmpk_lt_i32 s2, 0x8e
	s_cselect_b64 s[0:1], -1, 0
	s_or_b64 s[0:1], s[0:1], s[16:17]
	s_and_b64 vcc, exec, s[0:1]
	s_cbranch_vccnz .Lcv_done
	s_add_i32 s0, s2, 0xffffff72
	s_cmpk_gt_u32 s0, 0x24f
	s_cbranch_scc1 .Lcv_759
	s_waitcnt lgkmcnt(0)
	s_add_u32 s10, s14, 0x1b00000
	v_readlane_b32 s1, v250, 3
	s_addc_u32 s11, s15, 0
	s_lshl_b32 s0, s79, 3
	s_and_b32 s1, s1, 0xc0
	v_or_b32_e32 v54, s1, v148
	s_or_b32 s1, s0, 24
	s_and_b32 s12, s0, 0x1fffffe0
	s_mul_i32 s13, s1, 0x410
	s_or_b32 s1, s0, 1
	s_add_u32 s22, s14, 0x2800000
	s_addc_u32 s23, s15, 0
	s_waitcnt vmcnt(0)
	v_lshrrev_b32_e32 v2, 5, v148
	s_add_u32 s24, s14, 0x1d00000
	v_mul_u32_u24_e32 v2, 0xb00, v2
	s_movk_i32 s3, 0x60
	v_and_b32_e32 v0, 28, v165
	s_mov_b32 s21, 0
	v_lshl_add_u32 v53, v165, 2, 0
	s_mul_i32 s6, s79, 0x2080
	v_lshl_add_u32 v1, v54, 2, 0
	s_mul_i32 s7, s12, 0x410
	s_addc_u32 s25, s15, 0
	v_and_or_b32 v55, v165, s3, v2
	s_lshl_b32 s3, s2, 6
	s_lshl_b32 s4, s2, 4
	v_and_b32_e32 v52, 0xe0, v165
	v_mov_b32_e32 v49, 0
	s_mulk_i32 s1, 0x410
	s_addk_i32 s3, 0xdc80
	s_add_i32 s4, s4, 0x7fffd620
	s_add_i32 s5, s2, 0xffffff00
	v_add_u32_e32 v56, s6, v53
	v_add_u32_e32 v57, s7, v1
	s_movk_i32 s6, 0x7fff
	s_mov_b32 s7, 0xffff0000
	v_add_u32_e32 v58, s13, v1
	s_lshl_b32 s26, s12, 1
	v_lshlrev_b32_e32 v50, 2, v0
	v_mov_b32_e32 v59, 0x5800
	s_mov_b32 s27, s21
	s_branch .Lcv_749

; #define LAS __attribute__((address_space(3)))
; __device__ __forceinline__ void convert_tile(const float* __restrict__ W, int K, int ldn, const float* __restrict__ gain, bf16_t* WT, int pn, int k0, int kind, LAS unsigned char* lds, int wave, int lane) {
;     ...
;     u32x4* dst = (u32x4*)(WT + (size_t)(256 * pn + n) * K + k0 + 32 * hf);
; #pragma unroll
;     for (int j = 0; j < 4; ++j) dst[j] = o[j];
; }
; __device__ __forceinline__ void convert_weights(CArgsP a, LAS unsigned char* lds, int wave, int lane, int which, int gb, int NGB) {
;     unsigned char* ws = a->ws;
;     constexpr int I0 = 22 * 16, I1 = 4 * 44, I2 = 14 * 16, I3 = 4 * 16;
;     const int NIT = which == 0 ? I0 + I1 + I2 : I0 + I1 + I3;
;     for (int it = gb; it < NIT; it += NGB) {
.Lcv_748:
	v_lshl_add_u64 v[16:17], v[48:49], 1, v[16:17]
	s_addk_i32 s3, 0x1c80
	s_addk_i32 s4, 0x720
	v_lshl_add_u64 v[16:17], v[16:17], 0, s[26:27]
	s_cmpk_lt_i32 s5, 0x1de
	global_store_dwordx4 v[16:17], v[0:3], off
	global_store_dwordx4 v[16:17], v[4:7], off offset:16
	global_store_dwordx4 v[16:17], v[8:11], off offset:32
	global_store_dwordx4 v[16:17], v[12:15], off offset:48
	s_cbranch_scc0 .Lcv_759
; #define LAS __attribute__((address_space(3)))
; __device__ __forceinline__ unsigned pk2(float lo, float hi) { return f2bf(lo) | (f2bf(hi) << 16); }
; __device__ __forceinline__ void convert_tile(const float* __restrict__ W, int K, int ldn, const float* __restrict__ gain, bf16_t* WT, int pn, int k0, int kind, LAS unsigned char* lds, int wave, int lane) {
;     LAS float* T = (LAS float*)lds;
;     const int c = 4 * lane, q = c >> 5, db = 8 * pn + q;
;     int nsrc0, nvalid = 32;
;     if (kind == 0) nsrc0 = (q >> 2) * DFF + 128 * pn + 32 * (q & 3);
;     else if (kind == 1) nsrc0 = 32 * db;
;     else { const int l = 256 * pn + 64 * (q & 3) + 32 * (q >> 2); if (l < 1536) nsrc0 = l; else if (l < 3328) nsrc0 = l + 8; else { nsrc0 = 1536; nvalid = (l == 3328) ? 8 : 0; } }
;     const bool ok = (c & 31) < nvalid;
;     __syncthreads();
;     f32x4 v[8];
; #pragma unroll
;     for (int i = 0; i < 8; ++i) { const int kk = 8 * wave + i; v[i] = (f32x4){0.f, 0.f, 0.f, 0.f}; if (ok) v[i] = *(const f32x4*)(W + (size_t)(k0 + kk) * ldn + nsrc0 + (c & 31)); }
; #pragma unroll
;     for (int i = 0; i < 8; ++i) { const int kk = 8 * wave + i; f32x4 t = v[i]; if (gain) t = t * gain[k0 + kk]; *(LAS f32x4*)(T + kk * 260 + c) = t; }
;     __syncthreads();
;     const int tid = wave * 64 + lane, n = tid & 255, hf = tid >> 8;
;     u32x4 o[4];
; #pragma unroll
;     for (int j = 0; j < 4; ++j) {
;         const LAS float* sp = T + (32 * hf + 8 * j) * 260 + n;
;         o[j].x = pk2(sp[0 * 260], sp[1 * 260]); o[j].y = pk2(sp[2 * 260], sp[3 * 260]); o[j].z = pk2(sp[4 * 260], sp[5 * 260]); o[j].w = pk2(sp[6 * 260], sp[7 * 260]);
;     }
;     u32x4* dst = (u32x4*)(WT + (size_t)(256 * pn + n) * K + k0 + 32 * hf);
.Lcv_749:
	s_addk_i32 s5, 0x72
	s_cmpk_gt_i32 s5, 0x15f
	s_mov_b64 s[12:13], -1
	s_cbranch_scc0 .Lcv_755
	s_cmpk_gt_u32 s5, 0x20f
	s_cbranch_scc0 .Lcv_752
	s_load_dwordx2 s[28:29], s[18:19], 0x60
	s_and_b32 s12, s4, 0x7fffff00
	s_and_b32 s14, s3, 0x3c0
	v_or_b32_e32 v48, s12, v52
	s_add_i32 s20, s14, s0
	s_waitcnt lgkmcnt(0)
	v_lshl_add_u64 v[0:1], v[48:49], 2, s[28:29]
	v_mov_b32_e32 v51, v49
	s_waitcnt vmcnt(5)
	v_lshl_add_u64 v[24:25], v[0:1], 0, v[50:51]
	s_lshl_b64 s[28:29], s[20:21], 12
	v_lshl_add_u64 v[0:1], v[24:25], 0, s[28:29]
	s_or_b32 s28, s20, 1
	s_mov_b32 s29, s21
	s_lshl_b64 s[28:29], s[28:29], 12
	v_lshl_add_u64 v[4:5], v[24:25], 0, s[28:29]
	s_or_b32 s28, s20, 2
	s_mov_b32 s29, s21
	s_lshl_b64 s[28:29], s[28:29], 12
	v_lshl_add_u64 v[8:9], v[24:25], 0, s[28:29]
	s_or_b32 s28, s20, 3
	s_mov_b32 s29, s21
	s_lshl_b64 s[28:29], s[28:29], 12
	v_lshl_add_u64 v[12:13], v[24:25], 0, s[28:29]
	s_or_b32 s28, s20, 4
	s_mov_b32 s29, s21
	s_lshl_b64 s[28:29], s[28:29], 12
	v_lshl_add_u64 v[16:17], v[24:25], 0, s[28:29]
	s_or_b32 s28, s20, 5
	s_mov_b32 s29, s21
	s_lshl_b64 s[28:29], s[28:29], 12
	v_lshl_add_u64 v[20:21], v[24:25], 0, s[28:29]
	s_or_b32 s28, s20, 6
	s_mov_b32 s29, s21
	s_lshl_b64 s[28:29], s[28:29], 12
	s_or_b32 s20, s20, 7
	v_lshl_add_u64 v[26:27], v[24:25], 0, s[28:29]
	s_lshl_b64 s[28:29], s[20:21], 12
	s_waitcnt vmcnt(4)
	v_lshl_add_u64 v[28:29], v[24:25], 0, s[28:29]
	s_barrier
	global_load_dwordx4 v[0:3], v[0:1], off
	s_nop 0
	global_load_dwordx4 v[4:7], v[4:5], off
	s_nop 0
	global_load_dwordx4 v[8:11], v[8:9], off
	s_nop 0
	global_load_dwordx4 v[12:15], v[12:13], off
	s_nop 0
	global_load_dwordx4 v[16:19], v[16:17], off
	s_nop 0
	global_load_dwordx4 v[20:23], v[20:21], off
	s_nop 0
	global_load_dwordx4 v[24:27], v[26:27], off
	s_nop 0
	global_load_dwordx4 v[28:31], v[28:29], off
	v_or_b32_e32 v48, s12, v54
	s_mov_b64 s[12:13], 0
	s_waitcnt vmcnt(7)
	ds_write_b128 v56, v[0:3]
	s_waitcnt vmcnt(6)
	ds_write_b128 v56, v[4:7] offset:1040
	s_waitcnt vmcnt(5)
	ds_write_b128 v56, v[8:11] offset:2080
	s_waitcnt vmcnt(4)
	ds_write_b128 v56, v[12:15] offset:3120
	s_waitcnt vmcnt(3)
	ds_write_b128 v56, v[16:19] offset:4160
	s_waitcnt vmcnt(2)
	ds_write_b128 v56, v[20:23] offset:5200
	s_waitcnt vmcnt(1)
	ds_write_b128 v56, v[24:27] offset:6240
	s_waitcnt vmcnt(0)
	ds_write_b128 v56, v[28:31] offset:7280
	s_waitcnt lgkmcnt(0)
	s_barrier
	ds_read_b32 v0, v57
	ds_read_b32 v1, v57 offset:1040
	ds_read_b32 v2, v57 offset:2080
	ds_read_b32 v3, v57 offset:3120
	ds_read_b32 v4, v57 offset:4160
	ds_read_b32 v5, v57 offset:5200
	ds_read_b32 v6, v57 offset:6240
	ds_read_b32 v7, v57 offset:7280
	s_waitcnt lgkmcnt(7)
	v_bfe_u32 v8, v0, 16, 1
	s_waitcnt lgkmcnt(5)
	v_bfe_u32 v10, v2, 16, 1
	s_waitcnt lgkmcnt(3)
	v_bfe_u32 v12, v4, 16, 1
	s_waitcnt lgkmcnt(1)
	v_bfe_u32 v14, v6, 16, 1
	v_bfe_u32 v9, v1, 16, 1
	v_bfe_u32 v11, v3, 16, 1
	v_bfe_u32 v13, v5, 16, 1
	s_waitcnt lgkmcnt(0)
	v_bfe_u32 v15, v7, 16, 1
	v_add3_u32 v0, v0, v8, s6
	v_add3_u32 v2, v2, v10, s6
	v_add3_u32 v4, v4, v12, s6
	v_add3_u32 v6, v6, v14, s6
	v_add3_u32 v1, v1, v9, s6
	v_add3_u32 v3, v3, v11, s6
	v_add3_u32 v5, v5, v13, s6
	v_add3_u32 v7, v7, v15, s6
	v_lshrrev_b32_e32 v0, 16, v0
	v_lshrrev_b32_e32 v2, 16, v2
	v_lshrrev_b32_e32 v4, 16, v4
	v_lshrrev_b32_e32 v6, 16, v6
	v_and_or_b32 v0, v1, s7, v0
	v_and_or_b32 v1, v3, s7, v2
	v_and_or_b32 v2, v5, s7, v4
	v_and_or_b32 v3, v7, s7, v6
	ds_read_b32 v4, v57 offset:8320
	ds_read_b32 v5, v57 offset:9360
	ds_read_b32 v6, v57 offset:10400
	ds_read_b32 v7, v57 offset:11440
	ds_read_b32 v8, v57 offset:12480
	ds_read_b32 v9, v57 offset:13520
	ds_read_b32 v10, v57 offset:14560
	ds_read_b32 v11, v57 offset:15600
	s_waitcnt lgkmcnt(7)
	v_bfe_u32 v12, v4, 16, 1
	v_add3_u32 v4, v4, v12, s6
	s_waitcnt lgkmcnt(6)
	v_bfe_u32 v12, v5, 16, 1
	v_lshrrev_b32_e32 v4, 16, v4
	v_add3_u32 v5, v5, v12, s6
	v_and_or_b32 v4, v5, s7, v4
	s_waitcnt lgkmcnt(5)
	v_bfe_u32 v5, v6, 16, 1
	v_add3_u32 v5, v6, v5, s6
	s_waitcnt lgkmcnt(4)
	v_bfe_u32 v6, v7, 16, 1
	v_lshrrev_b32_e32 v5, 16, v5
	v_add3_u32 v6, v7, v6, s6
	v_and_or_b32 v5, v6, s7, v5
	s_waitcnt lgkmcnt(3)
	v_bfe_u32 v6, v8, 16, 1
	v_add3_u32 v6, v8, v6, s6
	s_waitcnt lgkmcnt(2)
	v_bfe_u32 v7, v9, 16, 1
	v_lshrrev_b32_e32 v6, 16, v6
	v_add3_u32 v7, v9, v7, s6
	v_and_or_b32 v6, v7, s7, v6
	s_waitcnt lgkmcnt(1)
	v_bfe_u32 v7, v10, 16, 1
	v_add3_u32 v7, v10, v7, s6
	s_waitcnt lgkmcnt(0)
	v_bfe_u32 v8, v11, 16, 1
	v_lshrrev_b32_e32 v7, 16, v7
	v_add3_u32 v8, v11, v8, s6
	v_and_or_b32 v7, v8, s7, v7
	ds_read_b32 v8, v57 offset:16640
	ds_read_b32 v9, v57 offset:17680
	ds_read_b32 v10, v57 offset:18720
	ds_read_b32 v11, v57 offset:19760
	ds_read_b32 v12, v57 offset:20800
	ds_read_b32 v13, v57 offset:21840
	ds_read_b32 v14, v57 offset:22880
	ds_read_b32 v15, v57 offset:23920
	s_waitcnt lgkmcnt(7)
	v_bfe_u32 v16, v8, 16, 1
	v_add3_u32 v8, v8, v16, s6
	s_waitcnt lgkmcnt(6)
	v_bfe_u32 v16, v9, 16, 1
	v_lshrrev_b32_e32 v8, 16, v8
	v_add3_u32 v9, v9, v16, s6
	v_and_or_b32 v8, v9, s7, v8
	s_waitcnt lgkmcnt(5)
	v_bfe_u32 v9, v10, 16, 1
	v_add3_u32 v9, v10, v9, s6
	s_waitcnt lgkmcnt(4)
	v_bfe_u32 v10, v11, 16, 1
	v_lshrrev_b32_e32 v9, 16, v9
	v_add3_u32 v10, v11, v10, s6
	v_and_or_b32 v9, v10, s7, v9
	s_waitcnt lgkmcnt(3)
	v_bfe_u32 v10, v12, 16, 1
	v_add3_u32 v10, v12, v10, s6
	s_waitcnt lgkmcnt(2)
	v_bfe_u32 v11, v13, 16, 1
	v_lshrrev_b32_e32 v10, 16, v10
	v_add3_u32 v11, v13, v11, s6
	v_and_or_b32 v10, v11, s7, v10
	s_waitcnt lgkmcnt(1)
	v_bfe_u32 v11, v14, 16, 1
	v_add3_u32 v11, v14, v11, s6
	s_waitcnt lgkmcnt(0)
	v_bfe_u32 v12, v15, 16, 1
	v_lshrrev_b32_e32 v11, 16, v11
	v_add3_u32 v12, v15, v12, s6
	v_and_or_b32 v11, v12, s7, v11
	ds_read_b32 v12, v58
	ds_read_b32 v13, v58 offset:1040
	ds_read_b32 v14, v58 offset:2080
	ds_read_b32 v15, v58 offset:3120
	ds_read_b32 v16, v58 offset:4160
	ds_read_b32 v17, v58 offset:5200
	ds_read_b32 v18, v58 offset:6240
	ds_read_b32 v19, v58 offset:7280
	s_waitcnt lgkmcnt(7)
	v_bfe_u32 v20, v12, 16, 1
	v_add3_u32 v12, v12, v20, s6
	s_waitcnt lgkmcnt(6)
	v_bfe_u32 v20, v13, 16, 1
	v_lshrrev_b32_e32 v12, 16, v12
	v_add3_u32 v13, v13, v20, s6
	v_and_or_b32 v12, v13, s7, v12
	s_waitcnt lgkmcnt(5)
	v_bfe_u32 v13, v14, 16, 1
	v_add3_u32 v13, v14, v13, s6
	s_waitcnt lgkmcnt(4)
	v_bfe_u32 v14, v15, 16, 1
	v_lshrrev_b32_e32 v13, 16, v13
	v_add3_u32 v14, v15, v14, s6
	v_and_or_b32 v13, v14, s7, v13
	s_waitcnt lgkmcnt(3)
	v_bfe_u32 v14, v16, 16, 1
	v_add3_u32 v14, v16, v14, s6
	s_waitcnt lgkmcnt(2)
	v_bfe_u32 v15, v17, 16, 1
	v_lshrrev_b32_e32 v14, 16, v14
	v_add3_u32 v15, v17, v15, s6
	v_and_or_b32 v14, v15, s7, v14
	s_waitcnt lgkmcnt(1)
	v_bfe_u32 v15, v18, 16, 1
	v_add3_u32 v15, v18, v15, s6
	s_waitcnt lgkmcnt(0)
	v_bfe_u32 v16, v19, 16, 1
	v_lshrrev_b32_e32 v15, 16, v15
	v_add3_u32 v16, v19, v16, s6
	v_and_or_b32 v15, v16, s7, v15
	v_lshlrev_b64 v[16:17], 11, v[48:49]
	v_lshl_add_u64 v[16:17], s[10:11], 0, v[16:17]
	v_mov_b32_e32 v48, s14

; __device__ __forceinline__ unsigned xb_ld(unsigned* p)              { return __hip_atomic_load(p, __ATOMIC_RELAXED, __HIP_MEMORY_SCOPE_AGENT); }
; __device__ __forceinline__ unsigned xb_add(unsigned* p, unsigned v) { return __hip_atomic_fetch_add(p, v, __ATOMIC_RELAXED, __HIP_MEMORY_SCOPE_AGENT); }
; __device__ __forceinline__ void xcd_barrier_complete(unsigned* bar, unsigned x, unsigned& nloc, unsigned& nx) {
;     const unsigned G = gridDim.x * gridDim.y * gridDim.z;
;     unsigned sum, cnt, mine, sp = 0u;
;     for (;;) {
;         sum = 0u; cnt = 0u; mine = 0u;
; #pragma unroll
;         for (unsigned j = 0; j < 16; ++j) { const unsigned c = xb_ld(&bar[XB_XCNT(j)]); sum += c; cnt += (c > 0u) ? 1u : 0u; mine = (j == x) ? c : mine; }
;         if (sum == G) break;
;         __builtin_amdgcn_s_sleep(1);
;         if ((++sp & 255u) == 0u) { if (xb_ld(&bar[XB_TMO])) break; if (sp > XB_SPIN_CAP) { atomicAdd(&bar[XB_TMO], 1u); break; } }
;     }
;     nloc = mine > 0u ? mine : 1u; nx = cnt > 0u ? cnt : 1u;
; }
; __device__ __forceinline__ void xcd_barrier(const XcdBarrier& b) {
;     asm volatile("s_waitcnt vmcnt(0)" ::: "memory");
;     __syncthreads();
;     if (threadIdx.x == 0) {
;         unsigned* bar = b.bar;
;         __builtin_amdgcn_s_waitcnt(0);
;         unsigned nloc = b.st[0], nx = b.st[1];
;         if (nloc == 0u) { xcd_barrier_complete(bar, b.x, nloc, nx); b.st[0] = nloc; b.st[1] = nx; }
;         const unsigned old = xb_add(&bar[XB_XSUB(b.x)], 1u);
;         const unsigned gen = old / nloc;
.Lcv_done:
.LBB0_539:
	s_mov_b64 s[12:13], s[92:93]
	s_getreg_b32 s0, hwreg(HW_REG_XCC_ID, 0, 4)
	s_waitcnt vmcnt(0)
	s_waitcnt vmcnt(0) lgkmcnt(0)
	s_barrier
	s_and_saveexec_b64 s[10:11], s[52:53]
	s_cbranch_execz .LBB0_591
	s_add_i32 s1, 0, 0x20040
	v_mov_b32_e32 v0, s1
	s_load_dwordx2 s[12:13], s[12:13], 0xf8
	s_waitcnt vmcnt(0) expcnt(0) lgkmcnt(0)
	ds_read_b32 v2, v0
	s_add_i32 s1, 0, 0x20044
	v_mov_b32_e32 v0, s1
	ds_read_b32 v0, v0
	s_and_b32 s0, s0, 15
	s_waitcnt lgkmcnt(1)
	v_cmp_ne_u32_e32 vcc, 0, v2
	s_cbranch_vccnz .LBB0_555
	s_add_u32 s14, s12, 0x80200
	s_addc_u32 s15, s13, 0
	s_add_u32 s16, s12, 0x80400
	s_addc_u32 s17, s13, 0
	s_add_u32 s18, s12, 0x80500
	s_addc_u32 s19, s13, 0
	s_add_u32 s20, s12, 0x80600
	s_addc_u32 s21, s13, 0
	s_add_u32 s22, s12, 0x80700
	s_addc_u32 s23, s13, 0
	s_add_u32 s24, s12, 0x80800
	s_addc_u32 s25, s13, 0
	s_add_u32 s26, s12, 0x80900
	s_addc_u32 s27, s13, 0
	s_add_u32 s38, s12, 0x80a00
	s_addc_u32 s39, s13, 0
	s_add_u32 s40, s12, 0x80b00
	s_addc_u32 s41, s13, 0
	s_add_u32 s42, s12, 0x80c00
	s_addc_u32 s43, s13, 0
	s_add_u32 s44, s12, 0x80d00
	s_addc_u32 s45, s13, 0
	s_add_u32 s46, s12, 0x80e00
	s_addc_u32 s47, s13, 0
	s_add_u32 s48, s12, 0x80f00
	s_addc_u32 s49, s13, 0
	s_add_u32 s50, s12, 0x81000
	s_addc_u32 s51, s13, 0
	s_add_u32 s54, s12, 0x81100
	s_addc_u32 s55, s13, 0
	s_add_u32 s56, s12, 0x81200
	s_addc_u32 s57, s13, 0
	s_mul_i32 s1, s61, s78
	s_add_u32 s58, s12, 0x81300
	s_mul_i32 s1, s1, s60
	s_addc_u32 s59, s13, 0
	s_mov_b32 s3, 1
	v_mov_b32_e32 v16, 0
	s_branch .LBB0_543

; #define LAS __attribute__((address_space(3)))
; __device__ __forceinline__ void convert_weights(CArgsP a, LAS unsigned char* lds, int wave, int lane, int which, int gb, int NGB) {
;     unsigned char* ws = a->ws;
;     constexpr int I0 = 22 * 16, I1 = 4 * 44, I2 = 14 * 16, I3 = 4 * 16;
;     const int NIT = which == 0 ? I0 + I1 + I2 : I0 + I1 + I3;
;     for (int it = gb; it < NIT; it += NGB) {
;         int r = it;
;         if (r < I0) { const int pn = r >> 4, kb = r & 15;
;             convert_tile(which == 0 ? a->in[8] : a->in[28], 1024, 5632, which == 0 ? a->in[7] : a->in[27], (bf16_t*)(ws + (which == 0 ? WS_W1I : WS_W2I)), pn, 64 * kb, 0, lds, wave, lane); continue; }
;         r -= I0;
;         if (r < I1) { const int pn = r / 44, kb = r % 44; convert_tile(which == 0 ? a->in[9] : a->in[29], DFF, 1024, nullptr, (bf16_t*)(ws + (which == 0 ? WS_W1O : WS_W2O)), pn, 64 * kb, 1, lds, wave, lane); continue; }
;         r -= I1;
;         if (which == 0) { const int pn = r >> 4, kb = r & 15; convert_tile(a->in[11], 1024, 3336, a->in[10], (bf16_t*)(ws + WS_WIN), pn, 64 * kb, 2, lds, wave, lane); }
;         else { const int pn = r >> 4, kb = r & 15; convert_tile(a->in[12], 1024, 1024, nullptr, (bf16_t*)(ws + WS_WOUT), pn, 64 * kb, 1, lds, wave, lane); }
; __global__ void __launch_bounds__(512, 2) mega_fwd(Args a_unused) {
;     ...
;       if (G == 256 && bx >= 134) convert_weights(a, lds, wave, lane, 1, bx - 134, 122); }
.LBB0_743:
	s_cmpk_eq_i32 s60, 0x100
	s_cselect_b64 s[66:67], -1, 0
	s_cmpk_lg_i32 s60, 0x100
	s_cselect_b64 s[16:17], -1, 0
	s_cmpk_lt_i32 s2, 0x7fff
	s_cselect_b64 s[0:1], -1, 0
	s_or_b64 s[0:1], s[0:1], s[16:17]
	s_and_b64 vcc, exec, s[0:1]
	s_cbranch_vccnz .LBB0_760
	s_add_i32 s0, s2, 0xffffff7a
	s_cmpk_gt_u32 s0, 0x24f
	s_cbranch_scc1 .LBB0_759
	s_waitcnt lgkmcnt(0)
	s_add_u32 s10, s14, 0x1b00000
	v_readlane_b32 s1, v250, 3
	s_addc_u32 s11, s15, 0
	s_lshl_b32 s0, s79, 3
	s_and_b32 s1, s1, 0xc0
	v_or_b32_e32 v54, s1, v148
	s_or_b32 s1, s0, 24
	s_and_b32 s12, s0, 0x1fffffe0
	s_mul_i32 s13, s1, 0x410
	s_or_b32 s1, s0, 1
	s_add_u32 s22, s14, 0x2800000
	s_addc_u32 s23, s15, 0
	s_waitcnt vmcnt(0)
	v_lshrrev_b32_e32 v2, 5, v148
	s_add_u32 s24, s14, 0x1d00000
	v_mul_u32_u24_e32 v2, 0xb00, v2
	s_movk_i32 s3, 0x60
	v_and_b32_e32 v0, 28, v165
	s_mov_b32 s21, 0
	v_lshl_add_u32 v53, v165, 2, 0
	s_mul_i32 s6, s79, 0x2080
	v_lshl_add_u32 v1, v54, 2, 0
	s_mul_i32 s7, s12, 0x410
	s_addc_u32 s25, s15, 0
	v_and_or_b32 v55, v165, s3, v2
	s_lshl_b32 s3, s2, 6
	s_lshl_b32 s4, s2, 4
	v_and_b32_e32 v52, 0xe0, v165
	v_mov_b32_e32 v49, 0
	s_mulk_i32 s1, 0x410
	s_addk_i32 s3, 0xde80
	s_add_i32 s4, s4, 0x7fffd6a0
	s_add_i32 s5, s2, 0xffffff00
	v_add_u32_e32 v56, s6, v53
	v_add_u32_e32 v57, s7, v1
	s_movk_i32 s6, 0x7fff
	s_mov_b32 s7, 0xffff0000
	v_add_u32_e32 v58, s13, v1
	s_lshl_b32 s26, s12, 1
	v_lshlrev_b32_e32 v50, 2, v0
	v_mov_b32_e32 v59, 0x5800
	s_mov_b32 s27, s21
	s_branch .LBB0_749
